# speedup vs baseline: 1.1359x; 1.0007x over previous
; __device__ __forceinline__ void e_phase(int zz, const Params& p, int lprev, int sprev, int lnext, int snext, char* shm) {
;     ...
;     for (int d = tid; d < 1024; d += NTHREADS) {
;       if (sprev >= 0) {
;         float g = 0.f;
;         for (int ks = 0; ks < 4; ++ks) g += p.modpart[(((long)ks * 4 + lprev) * 8 + b) * 9216 + sprev * 3072 + 2048 + d];
;         vec[d] = g;
;         vec[1024 + d] = p.norm_g[(lprev * 6 + 2 * sprev + 1) * 1024 + d];
;       }
;       if (snext >= 0) {
;         float s1 = 0.f, s0 = 0.f;
;         for (int ks = 0; ks < 4; ++ks) {
;           const float* mp = p.modpart + (((long)ks * 4 + lnext) * 8 + b) * 9216 + snext * 3072;
;           s0 += mp[d];
;           s1 += mp[1024 + d];
;         }
;         vec[2048 + d] = s1;
;         vec[3072 + d] = s0;
;         vec[4096 + d] = p.norm_g[(lnext * 6 + 2 * snext) * 1024 + d];
;       }
.LBB0_179:
	s_andn2_b64 vcc, exec, s[18:19]
	s_cbranch_vccnz .LBB0_181
	v_lshl_add_u64 v[4:5], s[6:7], 0, v[46:47]
	v_add_co_u32_e32 v82, vcc, 0x2000, v4
	s_nop 1
	v_addc_co_u32_e32 v83, vcc, 0, v5, vcc
	v_add_co_u32_e32 v84, vcc, 0x122000, v4
	s_nop 1
	v_addc_co_u32_e32 v85, vcc, 0, v5, vcc
	v_add_co_u32_e32 v86, vcc, 0x242000, v4
	s_nop 1
	v_addc_co_u32_e32 v87, vcc, 0, v5, vcc
	v_add_co_u32_e32 v88, vcc, 0x362000, v4
	s_nop 1
	v_addc_co_u32_e32 v89, vcc, 0, v5, vcc
	v_add_u32_e32 v90, s35, v3
	v_ashrrev_i32_e32 v91, 31, v90
	v_lshl_add_u64 v[90:91], v[90:91], 2, s[52:53]
	global_load_dword v92, v[82:83], off
	global_load_dword v93, v[84:85], off
	global_load_dword v94, v[86:87], off
	global_load_dword v95, v[88:89], off
	global_load_dword v96, v[90:91], off
	s_waitcnt vmcnt(0)
	v_add_f32_e32 v8, 0, v92
	v_add_f32_e32 v8, v8, v93
	v_add_f32_e32 v6, v8, v94
	v_add_f32_e32 v6, v6, v95
	ds_write2st64_b32 v2, v6, v96 offset1:16
.LBB0_181:
	s_andn2_b64 vcc, exec, s[16:17]
	s_cbranch_vccnz .LBB0_178
	v_lshl_add_u64 v[4:5], s[24:25], 0, v[46:47]
	v_add_co_u32_e32 v98, vcc, 0x1000, v4
	s_nop 1
	v_addc_co_u32_e32 v99, vcc, 0, v5, vcc
	v_add_co_u32_e32 v100, vcc, 0x120000, v4
	s_nop 1
	v_addc_co_u32_e32 v101, vcc, 0, v5, vcc
	v_add_co_u32_e32 v102, vcc, 0x121000, v4
	s_nop 1
	v_addc_co_u32_e32 v103, vcc, 0, v5, vcc
	v_add_co_u32_e32 v104, vcc, 0x240000, v4
	s_nop 1
	v_addc_co_u32_e32 v105, vcc, 0, v5, vcc
	v_add_co_u32_e32 v106, vcc, 0x241000, v4
	s_nop 1
	v_addc_co_u32_e32 v107, vcc, 0, v5, vcc
	v_add_co_u32_e32 v108, vcc, 0x360000, v4
	s_nop 1
	v_addc_co_u32_e32 v109, vcc, 0, v5, vcc
	v_add_co_u32_e32 v110, vcc, 0x361000, v4
	s_nop 1
	v_addc_co_u32_e32 v111, vcc, 0, v5, vcc
	v_add_u32_e32 v112, s30, v3
	v_ashrrev_i32_e32 v113, 31, v112
	v_lshl_add_u64 v[112:113], v[112:113], 2, s[52:53]
	global_load_dword v60, v[4:5], off
	global_load_dword v61, v[98:99], off
	global_load_dword v62, v[100:101], off
	global_load_dword v63, v[102:103], off
	global_load_dword v64, v[104:105], off
	global_load_dword v65, v[106:107], off
	global_load_dword v66, v[108:109], off
	global_load_dword v67, v[110:111], off
	global_load_dword v68, v[112:113], off
	s_waitcnt vmcnt(0)
	v_add_f32_e32 v8, 0, v60
	v_add_f32_e32 v9, 0, v61
	v_add_f32_e32 v8, v8, v62
	v_add_f32_e32 v9, v9, v63
	v_add_f32_e32 v8, v8, v64
	v_add_f32_e32 v9, v9, v65
	v_add_f32_e32 v6, v8, v66
	v_add_f32_e32 v4, v9, v67
	ds_write2st64_b32 v2, v4, v6 offset0:32 offset1:48
	ds_write_b32 v2, v68 offset:16384
	s_branch .LBB0_178

; __device__ __forceinline__ float bflo(unsigned u) { return __uint_as_float(u << 16); }
; __device__ __forceinline__ float bfhi(unsigned u) { return __uint_as_float(u & 0xffff0000u); }
; __device__ __forceinline__ void hgrn_scan(int zz, const Params& p) {
;   const int tid = TIDX;
;   for (int e = blockIdx.x * NTHREADS + tid; e < 98304; e += gridDim.x * NTHREADS) {
;     const int bh = e >> 11, vk = (e & 2047) * 4, k = vk & 127;
;     float S0 = 0.f, S1 = 0.f, S2 = 0.f, S3 = 0.f;
;     u16* hp = p.hst + (long)bh * 64 * 8192 + vk;
;     const float* gp = p.hG + (long)bh * 64 * 128 + k;
; #pragma unroll 4
;     for (int c = 0; c < 64; ++c) {
;       uint2 t = *(const uint2*)(hp + (long)c * 8192);
;       float4 g = *(const float4*)(gp + c * 128);
;       uint2 o;
;       o.x = pack2(S0, S1);
;       o.y = pack2(S2, S3);
;       *(uint2*)(hp + (long)c * 8192) = o;
;       S0 = g.x * S0 + bflo(t.x);
;       S1 = g.y * S1 + bfhi(t.x);
;       S2 = g.z * S2 + bflo(t.y);
;       S3 = g.w * S3 + bfhi(t.y);
;     }
;   }
; }
.LBB0_270:
	v_lshl_add_u64 v[16:17], v[2:3], 0, s[6:7]
	v_mov_b32_e32 v26, v16
	v_mov_b32_e32 v27, v17
	v_lshl_add_u64 v[28:29], v[16:17], 0, s[88:89]
	v_lshl_add_u64 v[30:31], v[16:17], 0, s[86:87]
	v_lshl_add_u64 v[32:33], v[30:31], 0, s[88:89]
	global_load_dwordx2 v[34:35], v[26:27], off
	global_load_dwordx4 v[42:45], v[4:5], off offset:-1544
	global_load_dwordx2 v[36:37], v[28:29], off
	global_load_dwordx4 v[46:49], v[4:5], off offset:-1032
	global_load_dwordx2 v[38:39], v[30:31], off
	global_load_dwordx4 v[50:53], v[4:5], off offset:-520
	global_load_dwordx2 v[40:41], v[32:33], off
	global_load_dwordx4 v[54:57], v[4:5], off offset:-8
.Lscan_loop:
	s_add_u32 s6, s6, 0x10000
	s_addc_u32 s7, s7, 0
	v_lshl_add_u64 v[16:17], v[2:3], 0, s[6:7]
	v_mov_b32_e32 v58, v16
	v_mov_b32_e32 v59, v17
	v_lshl_add_u64 v[60:61], v[16:17], 0, s[88:89]
	v_lshl_add_u64 v[62:63], v[16:17], 0, s[86:87]
	v_lshl_add_u64 v[64:65], v[62:63], 0, s[88:89]
	global_load_dwordx2 v[66:67], v[58:59], off
	global_load_dwordx4 v[74:77], v[4:5], off offset:504
	global_load_dwordx2 v[68:69], v[60:61], off
	global_load_dwordx4 v[78:81], v[4:5], off offset:1016
	global_load_dwordx2 v[70:71], v[62:63], off
	global_load_dwordx4 v[82:85], v[4:5], off offset:1528
	global_load_dwordx2 v[72:73], v[64:65], off
	global_load_dwordx4 v[86:89], v[4:5], off offset:2040
	s_waitcnt vmcnt(8)
	v_cvt_pk_bf16_f32 v20, v6, v7
	v_cvt_pk_bf16_f32 v21, v8, v9
	global_store_dwordx2 v[26:27], v[20:21], off
	v_lshlrev_b32_e32 v22, 16, v34
	v_and_b32_e32 v23, 0xffff0000, v34
	v_lshlrev_b32_e32 v24, 16, v35
	v_and_b32_e32 v25, 0xffff0000, v35
	v_pk_fma_f32 v[6:7], v[6:7], v[42:43], v[22:23]
	v_pk_fma_f32 v[8:9], v[8:9], v[44:45], v[24:25]
	v_cvt_pk_bf16_f32 v18, v6, v7
	v_cvt_pk_bf16_f32 v19, v8, v9
	global_store_dwordx2 v[28:29], v[18:19], off
	v_lshlrev_b32_e32 v22, 16, v36
	v_and_b32_e32 v23, 0xffff0000, v36
	v_lshlrev_b32_e32 v24, 16, v37
	v_and_b32_e32 v25, 0xffff0000, v37
	v_pk_fma_f32 v[6:7], v[6:7], v[46:47], v[22:23]
	v_pk_fma_f32 v[8:9], v[8:9], v[48:49], v[24:25]
	v_cvt_pk_bf16_f32 v20, v6, v7
	v_cvt_pk_bf16_f32 v21, v8, v9
	global_store_dwordx2 v[30:31], v[20:21], off
	v_lshlrev_b32_e32 v22, 16, v38
	v_and_b32_e32 v23, 0xffff0000, v38
	v_lshlrev_b32_e32 v24, 16, v39
	v_and_b32_e32 v25, 0xffff0000, v39
	v_pk_fma_f32 v[6:7], v[6:7], v[50:51], v[22:23]
	v_pk_fma_f32 v[8:9], v[8:9], v[52:53], v[24:25]
	v_cvt_pk_bf16_f32 v18, v6, v7
	v_cvt_pk_bf16_f32 v19, v8, v9
	global_store_dwordx2 v[32:33], v[18:19], off
	v_lshlrev_b32_e32 v22, 16, v40
	v_and_b32_e32 v23, 0xffff0000, v40
	v_lshlrev_b32_e32 v24, 16, v41
	v_and_b32_e32 v25, 0xffff0000, v41
	v_pk_fma_f32 v[6:7], v[6:7], v[54:55], v[22:23]
	v_pk_fma_f32 v[8:9], v[8:9], v[56:57], v[24:25]
	s_add_u32 s6, s6, 0x10000
	s_addc_u32 s7, s7, 0
	s_cmp_eq_u32 s6, 0x100000
	s_cbranch_scc1 .Lscan_last
	v_lshl_add_u64 v[16:17], v[2:3], 0, s[6:7]
	v_mov_b32_e32 v26, v16
	v_mov_b32_e32 v27, v17
	v_lshl_add_u64 v[28:29], v[16:17], 0, s[88:89]
	v_lshl_add_u64 v[30:31], v[16:17], 0, s[86:87]
	v_lshl_add_u64 v[32:33], v[30:31], 0, s[88:89]
	global_load_dwordx2 v[34:35], v[26:27], off
	global_load_dwordx4 v[42:45], v[4:5], off offset:2552
	global_load_dwordx2 v[36:37], v[28:29], off
	global_load_dwordx4 v[46:49], v[4:5], off offset:3064
	global_load_dwordx2 v[38:39], v[30:31], off
	global_load_dwordx4 v[50:53], v[4:5], off offset:3576
	global_load_dwordx2 v[40:41], v[32:33], off
	global_load_dwordx4 v[54:57], v[4:5], off offset:4088
	s_waitcnt vmcnt(8)
	v_cvt_pk_bf16_f32 v20, v6, v7
	v_cvt_pk_bf16_f32 v21, v8, v9
	global_store_dwordx2 v[58:59], v[20:21], off
	v_lshlrev_b32_e32 v22, 16, v66
	v_and_b32_e32 v23, 0xffff0000, v66
	v_lshlrev_b32_e32 v24, 16, v67
	v_and_b32_e32 v25, 0xffff0000, v67
	v_pk_fma_f32 v[6:7], v[6:7], v[74:75], v[22:23]
	v_pk_fma_f32 v[8:9], v[8:9], v[76:77], v[24:25]
	v_cvt_pk_bf16_f32 v18, v6, v7
	v_cvt_pk_bf16_f32 v19, v8, v9
	global_store_dwordx2 v[60:61], v[18:19], off
	v_lshlrev_b32_e32 v22, 16, v68
	v_and_b32_e32 v23, 0xffff0000, v68
	v_lshlrev_b32_e32 v24, 16, v69
	v_and_b32_e32 v25, 0xffff0000, v69
	v_pk_fma_f32 v[6:7], v[6:7], v[78:79], v[22:23]
	v_pk_fma_f32 v[8:9], v[8:9], v[80:81], v[24:25]
	v_cvt_pk_bf16_f32 v20, v6, v7
	v_cvt_pk_bf16_f32 v21, v8, v9
	global_store_dwordx2 v[62:63], v[20:21], off
	v_lshlrev_b32_e32 v22, 16, v70
	v_and_b32_e32 v23, 0xffff0000, v70
	v_lshlrev_b32_e32 v24, 16, v71
	v_and_b32_e32 v25, 0xffff0000, v71
	v_pk_fma_f32 v[6:7], v[6:7], v[82:83], v[22:23]
	v_pk_fma_f32 v[8:9], v[8:9], v[84:85], v[24:25]
	v_cvt_pk_bf16_f32 v18, v6, v7
	v_cvt_pk_bf16_f32 v19, v8, v9
	global_store_dwordx2 v[64:65], v[18:19], off
	v_lshlrev_b32_e32 v22, 16, v72
	v_and_b32_e32 v23, 0xffff0000, v72
	v_lshlrev_b32_e32 v24, 16, v73
	v_and_b32_e32 v25, 0xffff0000, v73
	v_pk_fma_f32 v[6:7], v[6:7], v[86:87], v[22:23]
	v_pk_fma_f32 v[8:9], v[8:9], v[88:89], v[24:25]
	v_lshl_add_u64 v[4:5], v[4:5], 0, s[12:13]
	v_lshl_add_u64 v[4:5], v[4:5], 0, s[12:13]
	s_branch .Lscan_loop
.Lscan_last:
	s_waitcnt vmcnt(0)
	v_cvt_pk_bf16_f32 v20, v6, v7
	v_cvt_pk_bf16_f32 v21, v8, v9
	global_store_dwordx2 v[58:59], v[20:21], off
	v_lshlrev_b32_e32 v22, 16, v66
	v_and_b32_e32 v23, 0xffff0000, v66
	v_lshlrev_b32_e32 v24, 16, v67
	v_and_b32_e32 v25, 0xffff0000, v67
	v_pk_fma_f32 v[6:7], v[6:7], v[74:75], v[22:23]
	v_pk_fma_f32 v[8:9], v[8:9], v[76:77], v[24:25]
	v_cvt_pk_bf16_f32 v18, v6, v7
	v_cvt_pk_bf16_f32 v19, v8, v9
	global_store_dwordx2 v[60:61], v[18:19], off
	v_lshlrev_b32_e32 v22, 16, v68
	v_and_b32_e32 v23, 0xffff0000, v68
	v_lshlrev_b32_e32 v24, 16, v69
	v_and_b32_e32 v25, 0xffff0000, v69
	v_pk_fma_f32 v[6:7], v[6:7], v[78:79], v[22:23]
	v_pk_fma_f32 v[8:9], v[8:9], v[80:81], v[24:25]
	v_cvt_pk_bf16_f32 v20, v6, v7
	v_cvt_pk_bf16_f32 v21, v8, v9
	global_store_dwordx2 v[62:63], v[20:21], off
	v_lshlrev_b32_e32 v22, 16, v70
	v_and_b32_e32 v23, 0xffff0000, v70
	v_lshlrev_b32_e32 v24, 16, v71
	v_and_b32_e32 v25, 0xffff0000, v71
	v_pk_fma_f32 v[6:7], v[6:7], v[82:83], v[22:23]
	v_pk_fma_f32 v[8:9], v[8:9], v[84:85], v[24:25]
	v_cvt_pk_bf16_f32 v18, v6, v7
	v_cvt_pk_bf16_f32 v19, v8, v9
	global_store_dwordx2 v[64:65], v[18:19], off
	v_lshlrev_b32_e32 v22, 16, v72
	v_and_b32_e32 v23, 0xffff0000, v72
	v_lshlrev_b32_e32 v24, 16, v73
	v_and_b32_e32 v25, 0xffff0000, v73
	v_pk_fma_f32 v[6:7], v[6:7], v[86:87], v[22:23]
	v_pk_fma_f32 v[8:9], v[8:9], v[88:89], v[24:25]
	v_add_u32_e32 v0, s8, v0
	s_mov_b32 s6, 0x17fff
	v_cmp_lt_i32_e32 vcc, s6, v0
	s_or_b64 s[4:5], vcc, s[4:5]
	v_add_u32_e32 v10, s9, v10
	s_andn2_b64 exec, exec, s[4:5]
	s_cbranch_execnz .LBB0_269
